# mixer C unit epilogue: four serialised subln loads issued together into free VGPR quads (was load, vmcnt(0), use, repeated)
# baseline (speedup 1.0000x reference)
; __device__ __forceinline__ float shx(float v, int mask, int lane) { return __builtin_bit_cast(float, __builtin_amdgcn_ds_bpermute((lane ^ mask) << 2, __builtin_bit_cast(int, v))); }
; __device__ __forceinline__ void attn_C5(const Ctx& a, LAS unsigned char* lds, int wave_s) {
;     ...
;         if (c == 0) { const float il = 1.f / l; float ss = 0.f;
; #pragma unroll
;             for (int i = 0; i < 4; ++i)
; #pragma unroll
;                 for (int r = 0; r < 16; ++r) { const float v = o[i][r] * il - park[(i * 16 + r) * 64 + lane]; o[i][r] = v; ss += v * v; }
;             ss += shx(ss, 32, lane);
;             const float rstd = (1.f - lam_init) / sqrtf(ss * (1.f / 128.f) + EPS);
; #pragma unroll
.LBB0_631:
	s_waitcnt lgkmcnt(0)
	s_barrier
	s_andn2_b64 vcc, exec, s[14:15]
	s_cbranch_vccnz .LBB0_540
	v_div_scale_f32 v3, s[12:13], v4, v4, 1.0
	v_rcp_f32_e32 v5, v3
	s_lshl_b64 s[4:5], s[4:5], 1
	s_add_u32 s2, s30, s4
	s_addc_u32 s5, s31, s5
	v_fma_f32 v6, -v3, v5, 1.0
	v_fmac_f32_e32 v5, v6, v5
	v_div_scale_f32 v6, vcc, 1.0, v4, 1.0
	v_mul_f32_e32 v7, v6, v5
	v_fma_f32 v8, -v3, v7, v6
	v_fmac_f32_e32 v7, v8, v5
	v_fma_f32 v3, -v3, v7, v6
	v_div_fmas_f32 v3, v3, v5, v7
	v_div_fixup_f32 v96, v3, v4, 1.0
	ds_read2st64_b32 v[118:119], v0 offset1:1
	ds_read2st64_b32 v[120:121], v0 offset0:2 offset1:3
	ds_read2st64_b32 v[128:129], v0 offset0:4 offset1:5
	ds_read2st64_b32 v[122:123], v0 offset0:6 offset1:7
	ds_read2st64_b32 v[130:131], v0 offset0:8 offset1:9
	ds_read2st64_b32 v[126:127], v0 offset0:10 offset1:11
	ds_read2st64_b32 v[132:133], v0 offset0:12 offset1:13
	s_waitcnt vmcnt(1)
	ds_read2st64_b32 v[154:155], v0 offset0:14 offset1:15
	ds_read2st64_b32 v[144:145], v0 offset0:16 offset1:17
	ds_read2st64_b32 v[134:135], v0 offset0:18 offset1:19
	ds_read2st64_b32 v[152:153], v0 offset0:20 offset1:21
	ds_read2st64_b32 v[142:143], v0 offset0:22 offset1:23
	ds_read2st64_b32 v[148:149], v0 offset0:24 offset1:25
	ds_read2st64_b32 v[150:151], v0 offset0:26 offset1:27
	ds_read2st64_b32 v[140:141], v0 offset0:28 offset1:29
	ds_read2st64_b32 v[146:147], v0 offset0:30 offset1:31
	ds_read2st64_b32 v[136:137], v0 offset0:32 offset1:33
	ds_read2st64_b32 v[138:139], v0 offset0:34 offset1:35
	ds_read2st64_b32 v[116:117], v0 offset0:36 offset1:37
	ds_read2st64_b32 v[4:5], v0 offset0:38 offset1:39
	ds_read2st64_b32 v[112:113], v0 offset0:40 offset1:41
	ds_read2st64_b32 v[114:115], v0 offset0:42 offset1:43
	ds_read2st64_b32 v[108:109], v0 offset0:44 offset1:45
	ds_read2st64_b32 v[110:111], v0 offset0:46 offset1:47
	ds_read2st64_b32 v[104:105], v0 offset0:48 offset1:49
	ds_read2st64_b32 v[106:107], v0 offset0:50 offset1:51
	ds_read2st64_b32 v[100:101], v0 offset0:52 offset1:53
	ds_read2st64_b32 v[102:103], v0 offset0:54 offset1:55
	ds_read2st64_b32 v[98:99], v0 offset0:56 offset1:57
	ds_read2st64_b32 v[6:7], v0 offset0:58 offset1:59
	ds_read2st64_b32 v[8:9], v0 offset0:62 offset1:63
	s_add_u32 s4, s2, s26
	s_addc_u32 s5, s5, 0
	s_waitcnt lgkmcnt(14)
	v_pk_fma_f32 v[66:67], v[66:67], v[96:97], v[120:121] op_sel_hi:[1,0,1] neg_lo:[0,0,1] neg_hi:[0,0,1]
	s_waitcnt lgkmcnt(1)
	v_pk_fma_f32 v[14:15], v[26:27], v[96:97], v[6:7] op_sel_hi:[1,0,1] neg_lo:[0,0,1] neg_hi:[0,0,1]
	ds_read2st64_b32 v[6:7], v0 offset0:60 offset1:61
	v_ashrrev_i32_e32 v0, 3, v2
	v_and_b32_e32 v10, -4, v0
	v_ashrrev_i32_e32 v11, 31, v10
	v_lshl_add_u64 v[12:13], v[10:11], 2, s[88:89]
	global_load_dwordx3 v[156:158], v[12:13], off
	v_or_b32_e32 v124, 3, v0
	v_ashrrev_i32_e32 v125, 31, v124
	v_lshl_add_u64 v[124:125], v[124:125], 2, s[88:89]
	global_load_dword v3, v[124:125], off
	global_load_dwordx3 v[160:162], v[12:13], off offset:32
	global_load_dword v159, v[124:125], off offset:32
	global_load_dwordx3 v[164:166], v[12:13], off offset:64
	global_load_dword v163, v[124:125], off offset:64
	global_load_dwordx3 v[168:170], v[12:13], off offset:96
	global_load_dword v167, v[124:125], off offset:96
	v_lshlrev_b32_e32 v0, 11, v2
	v_and_b32_e32 v0, 0xf800, v0
	v_lshl_add_u64 v[124:125], s[4:5], 0, v[0:1]
	v_pk_mul_f32 v[120:121], v[66:67], v[66:67]
	v_lshl_add_u64 v[10:11], v[10:11], 1, v[124:125]
	v_pk_fma_f32 v[36:37], v[36:37], v[96:97], v[116:117] op_sel_hi:[1,0,1] neg_lo:[0,0,1] neg_hi:[0,0,1]
	v_pk_fma_f32 v[44:45], v[44:45], v[96:97], v[108:109] op_sel_hi:[1,0,1] neg_lo:[0,0,1] neg_hi:[0,0,1]
	v_pk_fma_f32 v[18:19], v[18:19], v[96:97], v[106:107] op_sel_hi:[1,0,1] neg_lo:[0,0,1] neg_hi:[0,0,1]
	v_pk_mul_f32 v[108:109], v[44:45], v[44:45]
	v_pk_fma_f32 v[16:17], v[16:17], v[96:97], v[104:105] op_sel_hi:[1,0,1] neg_lo:[0,0,1] neg_hi:[0,0,1]
	v_pk_mul_f32 v[106:107], v[18:19], v[18:19]
	v_pk_mul_f32 v[104:105], v[16:17], v[16:17]
	v_pk_fma_f32 v[22:23], v[22:23], v[96:97], v[102:103] op_sel_hi:[1,0,1] neg_lo:[0,0,1] neg_hi:[0,0,1]
	v_pk_mul_f32 v[26:27], v[14:15], v[14:15]
	v_pk_mul_f32 v[102:103], v[22:23], v[22:23]
	s_waitcnt lgkmcnt(0)
	v_pk_fma_f32 v[6:7], v[28:29], v[96:97], v[6:7] op_sel_hi:[1,0,1] neg_lo:[0,0,1] neg_hi:[0,0,1]
	v_pk_fma_f32 v[8:9], v[30:31], v[96:97], v[8:9] op_sel_hi:[1,0,1] neg_lo:[0,0,1] neg_hi:[0,0,1]
	v_pk_mul_f32 v[28:29], v[6:7], v[6:7]
	v_pk_mul_f32 v[30:31], v[8:9], v[8:9]
	s_mov_b32 s2, 0x3f077f5a
	s_waitcnt vmcnt(7)
	v_mov_b32_e32 v2, v158
	s_waitcnt vmcnt(6)
	v_pk_mul_f32 v[66:67], v[66:67], v[2:3]
	v_pk_fma_f32 v[2:3], v[64:65], v[96:97], v[118:119] op_sel_hi:[1,0,1] neg_lo:[0,0,1] neg_hi:[0,0,1]
	s_waitcnt vmcnt(5)
	v_mov_b32_e32 v158, v162
	v_pk_mul_f32 v[124:125], v[2:3], v[2:3]
	v_pk_mul_f32 v[118:119], v[2:3], v[156:157]
	v_pk_fma_f32 v[2:3], v[70:71], v[96:97], v[122:123] op_sel_hi:[1,0,1] neg_lo:[0,0,1] neg_hi:[0,0,1]
	s_waitcnt vmcnt(3)
	v_mov_b32_e32 v162, v166
	v_pk_mul_f32 v[122:123], v[2:3], v[2:3]
	v_pk_mul_f32 v[64:65], v[2:3], v[158:159]
	v_pk_fma_f32 v[2:3], v[68:69], v[96:97], v[128:129] op_sel_hi:[1,0,1] neg_lo:[0,0,1] neg_hi:[0,0,1]
	s_waitcnt vmcnt(1)
; __device__ __forceinline__ float shx(float v, int mask, int lane) { return __builtin_bit_cast(float, __builtin_amdgcn_ds_bpermute((lane ^ mask) << 2, __builtin_bit_cast(int, v))); }
; __device__ __forceinline__ int crow(int r, int hi) { return (r & 3) + 8 * (r >> 2) + 4 * hi; }
; __device__ __forceinline__ void attn_C5(const Ctx& a, LAS unsigned char* lds, int wave_s) {
;     ...
;         if (c == 0) { const float il = 1.f / l; float ss = 0.f;
; #pragma unroll
;             for (int i = 0; i < 4; ++i)
; #pragma unroll
;                 for (int r = 0; r < 16; ++r) { const float v = o[i][r] * il - park[(i * 16 + r) * 64 + lane]; o[i][r] = v; ss += v * v; }
;             ss += shx(ss, 32, lane);
;             const float rstd = (1.f - lam_init) / sqrtf(ss * (1.f / 128.f) + EPS);
; #pragma unroll
;             for (int i = 0; i < 4; ++i)
; #pragma unroll
;                 for (int r = 0; r < 16; ++r) o[i][r] *= subln[32 * i + crow(r, hi)];
;             store_o<128>(o, rstd, O + ((size_t)b * SEQ + q0) * 1024 + h * 128, 1024, lane); }
	v_mov_b32_e32 v166, v170
	v_pk_mul_f32 v[128:129], v[2:3], v[2:3]
	v_pk_mul_f32 v[70:71], v[2:3], v[160:161]
	v_pk_fma_f32 v[2:3], v[74:75], v[96:97], v[126:127] op_sel_hi:[1,0,1] neg_lo:[0,0,1] neg_hi:[0,0,1]
	v_add_f32_e32 v0, v124, v125
	v_pk_mul_f32 v[126:127], v[2:3], v[2:3]
	v_pk_mul_f32 v[68:69], v[2:3], v[162:163]
	v_pk_fma_f32 v[2:3], v[72:73], v[96:97], v[130:131] op_sel_hi:[1,0,1] neg_lo:[0,0,1] neg_hi:[0,0,1]
	v_add_f32_e32 v0, v0, v120
	v_pk_mul_f32 v[130:131], v[2:3], v[2:3]
	v_pk_mul_f32 v[74:75], v[2:3], v[164:165]
	v_pk_fma_f32 v[2:3], v[78:79], v[96:97], v[154:155] op_sel_hi:[1,0,1] neg_lo:[0,0,1] neg_hi:[0,0,1]
	global_load_dwordx4 v[154:157], v[12:13], off offset:128
	global_load_dwordx4 v[226:229], v[12:13], off offset:160
	global_load_dwordx4 v[230:233], v[12:13], off offset:192
	global_load_dwordx4 v[234:237], v[12:13], off offset:224
	global_load_dwordx4 v[238:241], v[12:13], off offset:256
	v_pk_mul_f32 v[78:79], v[2:3], v[2:3]
	s_waitcnt vmcnt(1)
	v_pk_mul_f32 v[72:73], v[2:3], v[166:167]
	v_pk_fma_f32 v[2:3], v[76:77], v[96:97], v[132:133] op_sel_hi:[1,0,1] neg_lo:[0,0,1] neg_hi:[0,0,1]
	v_add_f32_e32 v0, v0, v121
	v_pk_mul_f32 v[132:133], v[2:3], v[2:3]
	v_pk_mul_f32 v[76:77], v[2:3], v[168:169]
	v_pk_fma_f32 v[2:3], v[50:51], v[96:97], v[134:135] op_sel_hi:[1,0,1] neg_lo:[0,0,1] neg_hi:[0,0,1]
	v_add_f32_e32 v0, v0, v128
	v_pk_mul_f32 v[50:51], v[2:3], v[2:3]
	v_add_f32_e32 v0, v0, v129
	v_add_f32_e32 v0, v0, v122
	v_add_f32_e32 v0, v0, v123
	v_add_f32_e32 v0, v0, v130
	v_add_f32_e32 v0, v0, v131
	v_add_f32_e32 v0, v0, v126
	v_add_f32_e32 v0, v0, v127
	v_add_f32_e32 v0, v0, v132
	v_add_f32_e32 v0, v0, v133
	v_add_f32_e32 v0, v0, v78
	v_add_f32_e32 v0, v0, v79
	s_waitcnt vmcnt(0)
	v_pk_mul_f32 v[134:135], v[2:3], v[156:157]
	v_pk_fma_f32 v[2:3], v[48:49], v[96:97], v[144:145] op_sel_hi:[1,0,1] neg_lo:[0,0,1] neg_hi:[0,0,1]
	s_nop 0
	v_pk_mul_f32 v[48:49], v[2:3], v[154:155]
	v_pk_mul_f32 v[144:145], v[2:3], v[2:3]
	v_pk_fma_f32 v[2:3], v[54:55], v[96:97], v[142:143] op_sel_hi:[1,0,1] neg_lo:[0,0,1] neg_hi:[0,0,1]
	v_add_f32_e32 v0, v0, v144
	v_pk_mul_f32 v[142:143], v[2:3], v[2:3]
	v_add_f32_e32 v0, v0, v145
	v_add_f32_e32 v0, v0, v50
	v_add_f32_e32 v0, v0, v51
	s_waitcnt vmcnt(0)
	v_pk_mul_f32 v[54:55], v[2:3], v[228:229]
	v_pk_fma_f32 v[2:3], v[52:53], v[96:97], v[152:153] op_sel_hi:[1,0,1] neg_lo:[0,0,1] neg_hi:[0,0,1]
	s_nop 0
	v_pk_mul_f32 v[52:53], v[2:3], v[226:227]
	v_pk_mul_f32 v[152:153], v[2:3], v[2:3]
	v_pk_fma_f32 v[2:3], v[58:59], v[96:97], v[150:151] op_sel_hi:[1,0,1] neg_lo:[0,0,1] neg_hi:[0,0,1]
	v_add_f32_e32 v0, v0, v152
	v_pk_mul_f32 v[150:151], v[2:3], v[2:3]
	v_add_f32_e32 v0, v0, v153
	v_add_f32_e32 v0, v0, v142
	v_add_f32_e32 v0, v0, v143
	s_waitcnt vmcnt(0)
	v_pk_mul_f32 v[58:59], v[2:3], v[232:233]
	v_pk_fma_f32 v[2:3], v[56:57], v[96:97], v[148:149] op_sel_hi:[1,0,1] neg_lo:[0,0,1] neg_hi:[0,0,1]
	s_nop 0
	v_pk_mul_f32 v[56:57], v[2:3], v[230:231]
	v_pk_mul_f32 v[148:149], v[2:3], v[2:3]
	v_pk_fma_f32 v[2:3], v[62:63], v[96:97], v[146:147] op_sel_hi:[1,0,1] neg_lo:[0,0,1] neg_hi:[0,0,1]
	v_add_f32_e32 v0, v0, v148
	v_pk_mul_f32 v[146:147], v[2:3], v[2:3]
	v_add_f32_e32 v0, v0, v149
	v_add_f32_e32 v0, v0, v150
	v_add_f32_e32 v0, v0, v151
	s_waitcnt vmcnt(0)
	v_pk_mul_f32 v[62:63], v[2:3], v[236:237]
	v_pk_fma_f32 v[2:3], v[60:61], v[96:97], v[140:141] op_sel_hi:[1,0,1] neg_lo:[0,0,1] neg_hi:[0,0,1]
	s_nop 0
	v_pk_mul_f32 v[60:61], v[2:3], v[234:235]
	v_pk_mul_f32 v[140:141], v[2:3], v[2:3]
	v_pk_fma_f32 v[2:3], v[34:35], v[96:97], v[138:139] op_sel_hi:[1,0,1] neg_lo:[0,0,1] neg_hi:[0,0,1]
	v_add_f32_e32 v0, v0, v140
	v_pk_mul_f32 v[138:139], v[2:3], v[2:3]
	v_add_f32_e32 v0, v0, v141
	v_add_f32_e32 v0, v0, v146
	v_add_f32_e32 v0, v0, v147
	s_waitcnt vmcnt(0)
	v_pk_mul_f32 v[34:35], v[2:3], v[240:241]
	v_pk_fma_f32 v[2:3], v[32:33], v[96:97], v[136:137] op_sel_hi:[1,0,1] neg_lo:[0,0,1] neg_hi:[0,0,1]
	s_nop 0
	v_pk_mul_f32 v[136:137], v[2:3], v[2:3]
	v_pk_mul_f32 v[32:33], v[2:3], v[238:239]
	v_pk_fma_f32 v[154:155], v[38:39], v[96:97], v[4:5] op_sel_hi:[1,0,1] neg_lo:[0,0,1] neg_hi:[0,0,1]
	global_load_dwordx4 v[2:5], v[12:13], off offset:288
	v_pk_mul_f32 v[38:39], v[154:155], v[154:155]
	v_add_f32_e32 v0, v0, v136
	v_add_f32_e32 v0, v0, v137
	v_add_f32_e32 v0, v0, v138
	v_add_f32_e32 v0, v0, v139
	s_waitcnt vmcnt(0)
	v_pk_mul_f32 v[4:5], v[154:155], v[4:5]
	v_pk_mul_f32 v[154:155], v[36:37], v[36:37]
	v_pk_mul_f32 v[2:3], v[36:37], v[2:3]
	v_pk_fma_f32 v[36:37], v[42:43], v[96:97], v[114:115] op_sel_hi:[1,0,1] neg_lo:[0,0,1] neg_hi:[0,0,1]
	global_load_dwordx4 v[114:117], v[12:13], off offset:320
	v_pk_mul_f32 v[156:157], v[36:37], v[36:37]
	v_add_f32_e32 v0, v0, v154
	v_add_f32_e32 v0, v0, v155
	v_add_f32_e32 v0, v0, v38
	v_add_f32_e32 v0, v0, v39
	s_waitcnt vmcnt(0)
	v_pk_mul_f32 v[42:43], v[36:37], v[116:117]
	v_pk_fma_f32 v[36:37], v[40:41], v[96:97], v[112:113] op_sel_hi:[1,0,1] neg_lo:[0,0,1] neg_hi:[0,0,1]
	v_pk_fma_f32 v[40:41], v[46:47], v[96:97], v[110:111] op_sel_hi:[1,0,1] neg_lo:[0,0,1] neg_hi:[0,0,1]
	global_load_dwordx4 v[110:113], v[12:13], off offset:352
	v_pk_mul_f32 v[116:117], v[36:37], v[36:37]
	v_pk_mul_f32 v[36:37], v[36:37], v[114:115]
	v_pk_mul_f32 v[114:115], v[40:41], v[40:41]
	v_add_f32_e32 v0, v0, v116
	v_add_f32_e32 v0, v0, v117
	v_add_f32_e32 v0, v0, v156
	v_add_f32_e32 v0, v0, v157
	v_add_f32_e32 v0, v0, v108
	v_add_f32_e32 v0, v0, v109
	v_add_f32_e32 v0, v0, v114
	v_add_f32_e32 v0, v0, v115
	v_add_f32_e32 v0, v0, v104
	v_add_f32_e32 v0, v0, v105
	v_add_f32_e32 v0, v0, v106
	v_add_f32_e32 v0, v0, v107
	s_waitcnt vmcnt(0)
	v_pk_mul_f32 v[110:111], v[44:45], v[110:111]
	global_load_dwordx4 v[44:47], v[12:13], off offset:384
	v_pk_mul_f32 v[40:41], v[40:41], v[112:113]
	s_waitcnt vmcnt(0)
	v_pk_mul_f32 v[112:113], v[18:19], v[46:47]
	v_pk_mul_f32 v[158:159], v[16:17], v[44:45]
	global_load_dwordx4 v[16:19], v[12:13], off offset:416
	global_load_dwordx4 v[44:47], v[12:13], off offset:448
	s_waitcnt vmcnt(1)
	v_pk_mul_f32 v[160:161], v[22:23], v[18:19]
	v_pk_fma_f32 v[18:19], v[20:21], v[96:97], v[100:101] op_sel_hi:[1,0,1] neg_lo:[0,0,1] neg_hi:[0,0,1]
	s_nop 0
	v_pk_mul_f32 v[20:21], v[18:19], v[18:19]
	v_pk_mul_f32 v[100:101], v[18:19], v[16:17]
	v_add_f32_e32 v0, v0, v20
	v_add_f32_e32 v0, v0, v21
	v_pk_fma_f32 v[16:17], v[24:25], v[96:97], v[98:99] op_sel_hi:[1,0,1] neg_lo:[0,0,1] neg_hi:[0,0,1]
	v_add_f32_e32 v0, v0, v102
	v_pk_mul_f32 v[18:19], v[16:17], v[16:17]
	v_add_f32_e32 v0, v0, v103
	v_add_f32_e32 v0, v0, v18
	v_add_f32_e32 v0, v0, v19
	v_add_f32_e32 v0, v0, v26
	v_add_f32_e32 v0, v0, v27
	v_add_f32_e32 v0, v0, v28
	v_add_f32_e32 v0, v0, v29
	v_add_f32_e32 v0, v0, v30
	v_add_f32_e32 v0, v0, v31
	s_waitcnt vmcnt(0)
	v_pk_mul_f32 v[44:45], v[16:17], v[44:45]
	ds_bpermute_b32 v16, v97, v0
	s_waitcnt lgkmcnt(0)
	v_add_f32_e32 v0, v0, v16
	v_fmamk_f32 v0, v0, 0x3c000000, v196
	v_cmp_gt_f32_e32 vcc, s3, v0
	v_mul_f32_e32 v16, 0x4f800000, v0
	s_nop 0
	v_cndmask_b32_e32 v0, v0, v16, vcc
	v_sqrt_f32_e32 v16, v0
	s_nop 0
	v_add_u32_e32 v17, -1, v16
	v_fma_f32 v18, -v17, v16, v0
	v_cmp_ge_f32_e64 s[4:5], 0, v18
	v_add_u32_e32 v18, 1, v16
	s_nop 0
	v_cndmask_b32_e64 v17, v16, v17, s[4:5]
	v_fma_f32 v16, -v18, v16, v0
	v_cmp_lt_f32_e64 s[4:5], 0, v16
	s_nop 1
	v_cndmask_b32_e64 v16, v17, v18, s[4:5]
	v_mul_f32_e32 v17, 0x37800000, v16
	v_cndmask_b32_e32 v16, v16, v17, vcc
	v_cmp_class_f32_e32 vcc, v0, v197
	s_nop 1
	v_cndmask_b32_e32 v0, v16, v0, vcc
	v_div_scale_f32 v16, s[4:5], v0, v0, s2
	v_rcp_f32_e32 v17, v16
	s_nop 0
	v_fma_f32 v18, -v16, v17, 1.0
	v_fmac_f32_e32 v17, v18, v17
	v_div_scale_f32 v18, vcc, s2, v0, s2
	v_mul_f32_e32 v19, v18, v17
	v_fma_f32 v20, -v16, v19, v18
	v_fmac_f32_e32 v19, v20, v17
	v_fma_f32 v16, -v16, v19, v18
	v_div_fmas_f32 v16, v16, v17, v19
	v_div_fixup_f32 v0, v16, v0, s2
	v_pk_mul_f32 v[16:17], v[118:119], v[0:1] op_sel_hi:[1,0]
	v_pk_mul_f32 v[18:19], v[66:67], v[0:1] op_sel_hi:[1,0]
	v_cvt_pk_bf16_f32 v16, v16, v17
	v_cvt_pk_bf16_f32 v17, v18, v19
	v_pk_mul_f32 v[18:19], v[70:71], v[0:1] op_sel_hi:[1,0]
	v_pk_mul_f32 v[20:21], v[0:1], v[64:65] op_sel_hi:[0,1]
	v_cvt_pk_bf16_f32 v18, v18, v19
	v_cvt_pk_bf16_f32 v19, v20, v21
	v_pk_mul_f32 v[20:21], v[0:1], v[74:75] op_sel_hi:[0,1]
	v_pk_mul_f32 v[22:23], v[0:1], v[68:69] op_sel_hi:[0,1]
	v_cvt_pk_bf16_f32 v20, v20, v21
	v_cvt_pk_bf16_f32 v21, v22, v23
	v_pk_mul_f32 v[22:23], v[0:1], v[76:77] op_sel_hi:[0,1]
	v_pk_mul_f32 v[24:25], v[0:1], v[72:73] op_sel_hi:[0,1]
	v_pk_mul_f32 v[32:33], v[0:1], v[32:33] op_sel_hi:[0,1]
	v_pk_mul_f32 v[34:35], v[0:1], v[34:35] op_sel_hi:[0,1]
	v_pk_mul_f32 v[2:3], v[0:1], v[2:3] op_sel_hi:[0,1]
	v_cvt_pk_bf16_f32 v22, v22, v23
	v_cvt_pk_bf16_f32 v23, v24, v25
	v_pk_mul_f32 v[24:25], v[0:1], v[48:49] op_sel_hi:[0,1]
	v_pk_mul_f32 v[26:27], v[0:1], v[134:135] op_sel_hi:[0,1]
	v_cvt_pk_bf16_f32 v32, v32, v33
	v_cvt_pk_bf16_f32 v33, v34, v35
	v_cvt_pk_bf16_f32 v34, v2, v3
	v_pk_mul_f32 v[2:3], v[0:1], v[4:5] op_sel_hi:[0,1]
	v_cvt_pk_bf16_f32 v24, v24, v25
	v_cvt_pk_bf16_f32 v25, v26, v27
	v_pk_mul_f32 v[26:27], v[0:1], v[52:53] op_sel_hi:[0,1]
	v_pk_mul_f32 v[28:29], v[0:1], v[54:55] op_sel_hi:[0,1]
	v_cvt_pk_bf16_f32 v35, v2, v3
	v_pk_mul_f32 v[2:3], v[0:1], v[36:37] op_sel_hi:[0,1]
	v_cvt_pk_bf16_f32 v26, v26, v27
	v_cvt_pk_bf16_f32 v27, v28, v29
	v_pk_mul_f32 v[28:29], v[0:1], v[56:57] op_sel_hi:[0,1]
	v_pk_mul_f32 v[30:31], v[0:1], v[58:59] op_sel_hi:[0,1]
	v_cvt_pk_bf16_f32 v36, v2, v3
	v_pk_mul_f32 v[2:3], v[0:1], v[42:43] op_sel_hi:[0,1]
	v_cvt_pk_bf16_f32 v28, v28, v29
	v_cvt_pk_bf16_f32 v29, v30, v31
	v_pk_mul_f32 v[30:31], v[0:1], v[60:61] op_sel_hi:[0,1]
	v_pk_mul_f32 v[38:39], v[0:1], v[62:63] op_sel_hi:[0,1]
	v_cvt_pk_bf16_f32 v37, v2, v3
	v_pk_mul_f32 v[2:3], v[0:1], v[110:111] op_sel_hi:[0,1]
	v_cvt_pk_bf16_f32 v30, v30, v31
	v_cvt_pk_bf16_f32 v31, v38, v39
	v_cvt_pk_bf16_f32 v38, v2, v3
	v_pk_mul_f32 v[2:3], v[0:1], v[40:41] op_sel_hi:[0,1]
	v_cvt_pk_bf16_f32 v39, v2, v3
	v_pk_mul_f32 v[2:3], v[0:1], v[158:159] op_sel_hi:[0,1]
	v_cvt_pk_bf16_f32 v40, v2, v3
	v_pk_mul_f32 v[2:3], v[0:1], v[112:113] op_sel_hi:[0,1]
	v_cvt_pk_bf16_f32 v41, v2, v3
	v_pk_mul_f32 v[2:3], v[0:1], v[100:101] op_sel_hi:[0,1]
	v_cvt_pk_bf16_f32 v42, v2, v3
	v_pk_mul_f32 v[2:3], v[0:1], v[160:161] op_sel_hi:[0,1]
	v_cvt_pk_bf16_f32 v43, v2, v3
	v_pk_mul_f32 v[2:3], v[0:1], v[44:45] op_sel_hi:[0,1]
	v_cvt_pk_bf16_f32 v44, v2, v3
	v_pk_mul_f32 v[2:3], v[14:15], v[46:47]
	s_nop 0
	v_pk_mul_f32 v[2:3], v[0:1], v[2:3] op_sel_hi:[0,1]
	v_cvt_pk_bf16_f32 v45, v2, v3
	global_load_dwordx4 v[2:5], v[12:13], off offset:480
	s_nop 0
	global_store_dwordx2 v[10:11], v[16:17], off
	global_store_dwordx2 v[10:11], v[18:19], off offset:16
	global_store_dwordx2 v[10:11], v[20:21], off offset:32
	global_store_dwordx2 v[10:11], v[22:23], off offset:48
	global_store_dwordx2 v[10:11], v[24:25], off offset:64
	global_store_dwordx2 v[10:11], v[26:27], off offset:80
	global_store_dwordx2 v[10:11], v[28:29], off offset:96
	global_store_dwordx2 v[10:11], v[30:31], off offset:112
	global_store_dwordx2 v[10:11], v[32:33], off offset:128
	global_store_dwordx2 v[10:11], v[34:35], off offset:144
	global_store_dwordx2 v[10:11], v[36:37], off offset:160
	global_store_dwordx2 v[10:11], v[38:39], off offset:176
	global_store_dwordx2 v[10:11], v[40:41], off offset:192
	global_store_dwordx2 v[10:11], v[42:43], off offset:208
	global_store_dwordx2 v[10:11], v[44:45], off offset:224
	s_waitcnt vmcnt(15)
	v_pk_mul_f32 v[2:3], v[6:7], v[2:3]
	v_pk_mul_f32 v[4:5], v[8:9], v[4:5]
	v_pk_mul_f32 v[2:3], v[0:1], v[2:3] op_sel_hi:[0,1]
	v_pk_mul_f32 v[4:5], v[0:1], v[4:5] op_sel_hi:[0,1]
	v_cvt_pk_bf16_f32 v2, v2, v3
	v_cvt_pk_bf16_f32 v3, v4, v5
	global_store_dwordx2 v[10:11], v[2:3], off offset:240
	s_branch .LBB0_540
